# attention loops: the LDS-store wait sits directly before the loop-back barrier so the rotated scalar head overlaps the ds_write latency
# baseline (speedup 1.0000x reference)
.Lwh500:
	s_add_i32 s7, s7, 64
	s_add_i32 s0, s21, s22
	s_cmp_lg_u32 s0, 4
	v_subrev_u32_e32 v197, 64, v197
	v_mov_b32_e32 v198, v199
	s_cbranch_scc0 .Lwh_exitb
	s_mov_b64 s[2:3], s[14:15]
	s_mov_b32 s8, s22
	s_add_i32 s0, s8, 2
	s_cmp_lt_i32 s0, s18
	s_cselect_b64 s[12:13], -1, 0
	s_cmp_ge_i32 s0, s18
	s_cbranch_scc1 .Lwh491
	s_add_i32 s1, s6, s8
	s_add_i32 s4, s21, s8
	s_add_i32 s1, s1, 2
	s_add_i32 s4, s4, 34
	s_cmp_lt_i32 s0, s27
	s_cselect_b32 s0, s1, s4
	v_lshl_add_u32 v14, s0, 6, v194
	v_ashrrev_i32_e32 v15, 31, v14
	v_lshlrev_b64 v[14:15], 9, v[14:15]
	v_lshl_add_u64 v[14:15], v[190:191], 0, v[14:15]
	global_load_dwordx4 v[184:187], v[14:15], off

.Lwh495:
	s_bitcmp1_b32 s22, 0
	s_cselect_b32 s23, 0x2400, 0
	s_add_i32 s30, s23, 0
	s_bitcmp1_b32 s8, 0
	s_cselect_b32 s28, 0x2400, 0
	s_and_b64 s[4:5], s[2:3], s[14:15]
	s_add_i32 s29, s28, 0
	s_andn2_b64 vcc, exec, s[4:5]
	s_mov_b64 s[4:5], -1
	s_waitcnt lgkmcnt(0)
	s_barrier
	s_cbranch_vccnz .LBB0_502
	s_branch .LBB0_513
.Lwh_exitb:
	s_waitcnt lgkmcnt(0)
	s_barrier

.LBB0_543:
	v_add_f32_e32 v39, v129, v130
	v_add_f32_e32 v39, v110, v39
	v_add_f32_e32 v41, v147, v148
	v_exp_f32_e32 v37, v47
	v_exp_f32_e32 v35, v63
	v_exp_f32_e32 v40, v52
	v_exp_f32_e32 v38, v64
	v_exp_f32_e32 v34, v66
	v_exp_f32_e32 v124, v67
	v_exp_f32_e32 v36, v68
	v_exp_f32_e32 v125, v69
	v_exp_f32_e32 v129, v55
	v_exp_f32_e32 v130, v57
	v_add_f32_e32 v110, v39, v41
	v_exp_f32_e32 v39, v70
	v_exp_f32_e32 v41, v71
	v_exp_f32_e32 v122, v76
	v_exp_f32_e32 v123, v77
	s_andn2_b64 vcc, exec, s[20:21]
	s_waitcnt vmcnt(0)
	ds_write_b128 v111, v[106:109] offset:18432
	s_cbranch_vccz .Ldr_exit
	s_mov_b32 s25, s26
	s_add_i32 s27, s25, 3
	s_add_i32 s28, s24, s25
	s_cmp_lt_u32 s27, s7
	s_cselect_b64 s[2:3], -1, 0
	s_cbranch_scc0 .Ldr_nol
	s_add_i32 s4, s28, 35
	s_cmp_lt_u32 s27, s23
	s_cselect_b32 s4, s27, s4
	v_lshl_add_u32 v48, s4, 6, v117
	v_ashrrev_i32_e32 v49, 31, v48
	v_lshlrev_b64 v[48:49], 8, v[48:49]
	v_lshl_add_u64 v[48:49], v[112:113], 0, v[48:49]
	global_load_dwordx4 v[98:101], v[48:49], off
.Ldr_nol:
	s_waitcnt lgkmcnt(0)
	s_barrier
	s_branch .LBB0_537
